# FFN norm of the slab-1 rows whose out-GEMM tiles are all in the first round runs on idle workgroups during that GEMM's tail round (counter + write-through stores)
# baseline (speedup 1.0000x reference)
;     __device__ __forceinline__ void operator()(const f32x4 (&acc)[2][2][4][2], const Unit& u, int wr, int wc, int fr, int fq) const {
;         const int col0 = u.pn * BM + wc * 32 + 4 * fq;
; #pragma unroll
;         for (int ai = 0; ai < 2; ++ai) {
;             const int grb = row_base + u.pm * BM + ai * HALF + wr * 64;
;             const int seq = grb < MP ? (grb >> 11) : NPB + ((grb - MP) >> 6);
;             const float* gp = gate + (size_t)seq * (6 * DM) + col0;
;             f32x4 gv[2][2];
; #pragma unroll
;             for (int bj = 0; bj < 2; ++bj)
; #pragma unroll
;                 for (int n = 0; n < 2; ++n) gv[bj][n] = *(const f32x4*)(gp + bj * HALF + n * 16);
;             if (u.part == 0) {
; #pragma unroll
;                 for (int mp = 0; mp < 2; ++mp) {
;                 f32x4 xv[2][2][2];
; #pragma unroll
;                 for (int mm = 0; mm < 2; ++mm) { const int gr = grb + (2 * mp + mm) * 16 + fr;
;                     const float* xr = (gr < MP ? xin_p + (size_t)gr * DM : xin_s + (size_t)(gr - MP) * DM) + col0;
; #pragma unroll
;                     for (int bj = 0; bj < 2; ++bj)
; #pragma unroll
;                         for (int n = 0; n < 2; ++n) xv[mm][bj][n] = *(const f32x4*)(xr + bj * HALF + n * 16); }
; #pragma unroll
;                 for (int mm = 0; mm < 2; ++mm) { const int m = 2 * mp + mm; const int gr = grb + m * 16 + fr; float* orow = out + (size_t)gr * DM + col0;
; #pragma unroll
;                     for (int bj = 0; bj < 2; ++bj)
; #pragma unroll
;                         for (int n = 0; n < 2; ++n) *(f32x4*)(orow + bj * HALF + n * 16) = xv[mm][bj][n] + gv[bj][n] * acc[ai][bj][m][n]; }
.Lks6_done:
	s_lshl_b32 s15, s38, 8
	s_add_i32 s17, s36, s15
	s_cmp_eq_u32 s100, 2
	s_cselect_b32 s39, 0x80, 0
	s_add_i32 s17, s17, s39
	s_add_i32 s39, s17, 0xffff8000
	s_lshr_b32 s39, s39, 6
	s_ashr_i32 s38, s17, 11
	s_add_i32 s39, s39, 16
	s_cmp_lt_i32 s17, 0x8000
	v_or_b32_e32 v182, s17, v169
	s_mov_b32 s17, 0x8000
	v_add_u32_e32 v0, 0xffff8000, v182
	v_cmp_gt_i32_e32 vcc, s17, v182
	s_cselect_b32 s38, s38, s39
	v_ashrrev_i32_e32 v183, 31, v182
	v_cndmask_b32_e32 v146, v0, v182, vcc
	v_mov_b32_e32 v0, s35
	v_mov_b32_e32 v148, s31
	v_lshl_or_b32 v130, s40, 8, v191
	s_mul_hi_i32 s39, s38, 0x6000
	s_mulk_i32 s38, 0x6000
	v_readlane_b32 s28, v255, 25
	v_cndmask_b32_e32 v147, 0, v183, vcc
	v_cndmask_b32_e32 v149, v0, v148, vcc
	v_mov_b32_e32 v0, s34
	v_mov_b32_e32 v148, s30
	v_ashrrev_i32_e32 v131, 31, v130
	s_add_u32 s38, s28, s38
	v_readlane_b32 s28, v255, 27
	v_cndmask_b32_e32 v148, v0, v148, vcc
	v_lshlrev_b64 v[146:147], 12, v[146:147]
	s_addc_u32 s39, s28, s39
	v_lshlrev_b64 v[180:181], 2, v[130:131]
	v_lshl_add_u64 v[146:147], v[148:149], 0, v[146:147]
	v_lshl_add_u64 v[130:131], s[38:39], 0, v[180:181]
	v_lshl_add_u64 v[146:147], v[146:147], 0, v[180:181]
	global_load_dwordx4 v[142:145], v[130:131], off
	global_load_dwordx4 v[138:141], v[130:131], off offset:64
	global_load_dwordx4 v[134:137], v[130:131], off offset:512
	s_nop 0
	global_load_dwordx4 v[130:133], v[130:131], off offset:576
	s_nop 0
	global_load_dwordx4 v[158:161], v[146:147], off
	global_load_dwordx4 v[154:157], v[146:147], off offset:64
	global_load_dwordx4 v[150:153], v[146:147], off offset:512
	s_nop 0
	global_load_dwordx4 v[146:149], v[146:147], off offset:576
	v_or_b32_e32 v186, 16, v182
	s_movk_i32 s17, 0x7fff
	v_cmp_lt_i32_e32 vcc, s17, v186
	s_and_saveexec_b64 s[38:39], vcc
	s_xor_b64 s[38:39], exec, s[38:39]
	v_add_u32_e32 v0, 0xffff8010, v182
	v_lshlrev_b64 v[170:171], 12, v[0:1]
	v_mov_b32_e32 v187, v1
	v_lshl_add_u64 v[188:189], s[34:35], 0, v[170:171]
	v_lshlrev_b64 v[184:185], 12, v[186:187]
	s_andn2_saveexec_b64 s[38:39], s[38:39]
	v_ashrrev_i32_e32 v187, 31, v186
	v_lshlrev_b64 v[184:185], 12, v[186:187]
	v_lshl_add_u64 v[188:189], s[30:31], 0, v[184:185]
	s_or_b64 exec, exec, s[38:39]
	v_lshl_add_u64 v[170:171], v[188:189], 0, v[180:181]
	global_load_dwordx4 v[186:189], v[170:171], off
	global_load_dwordx4 v[216:219], v[170:171], off offset:64
	global_load_dwordx4 v[220:223], v[170:171], off offset:512
	global_load_dwordx4 v[224:227], v[170:171], off offset:576
	v_lshlrev_b64 v[170:171], 12, v[182:183]
	s_waitcnt vmcnt(0)
	v_pk_fma_f32 v[148:149], v[116:117], v[132:133], v[148:149]
	v_or_b32_e32 v116, 32, v182
	s_mov_b32 s17, 0x8000
	v_pk_fma_f32 v[118:119], v[118:119], v[134:135], v[150:151]
	v_add_u32_e32 v0, 0xffff8020, v182
	v_lshl_add_u64 v[150:151], s[24:25], 0, v[170:171]
	v_ashrrev_i32_e32 v117, 31, v116
	v_cmp_gt_i32_e32 vcc, s17, v116
	v_pk_fma_f32 v[128:129], v[128:129], v[144:145], v[160:161]
	v_pk_fma_f32 v[126:127], v[126:127], v[142:143], v[158:159]
	v_pk_fma_f32 v[124:125], v[124:125], v[140:141], v[156:157]
	v_pk_fma_f32 v[122:123], v[122:123], v[138:139], v[154:155]
	v_pk_fma_f32 v[120:121], v[120:121], v[136:137], v[152:153]
	v_mov_b32_e32 v154, s35
	v_mov_b32_e32 v155, s31
	v_mov_b32_e32 v156, s34
	v_mov_b32_e32 v157, s30
	v_lshl_add_u64 v[150:151], v[150:151], 0, v[180:181]
	v_cndmask_b32_e32 v153, 0, v117, vcc
	v_cndmask_b32_e32 v152, v0, v116, vcc
	v_pk_fma_f32 v[146:147], v[114:115], v[130:131], v[146:147]
	v_lshl_add_u64 v[114:115], s[24:25], 0, v[184:185]
	v_cndmask_b32_e32 v155, v154, v155, vcc
	v_cndmask_b32_e32 v154, v156, v157, vcc
	global_store_dwordx4 v[150:151], v[126:129], off sc0 sc1
	global_store_dwordx4 v[150:151], v[122:125], off offset:64 sc0 sc1
	global_store_dwordx4 v[150:151], v[118:121], off offset:512 sc0 sc1
	global_store_dwordx4 v[150:151], v[146:149], off offset:576 sc0 sc1
	v_lshl_add_u64 v[114:115], v[114:115], 0, v[180:181]
	v_lshlrev_b64 v[118:119], 12, v[152:153]
	v_lshl_add_u64 v[118:119], v[154:155], 0, v[118:119]
	v_lshl_add_u64 v[118:119], v[118:119], 0, v[180:181]
	s_movk_i32 s17, 0x7fff
	v_pk_fma_f32 v[112:113], v[112:113], v[144:145], v[188:189]
	v_pk_fma_f32 v[110:111], v[110:111], v[142:143], v[186:187]
	v_pk_fma_f32 v[108:109], v[108:109], v[140:141], v[218:219]
	v_pk_fma_f32 v[106:107], v[106:107], v[138:139], v[216:217]
	v_pk_fma_f32 v[104:105], v[104:105], v[136:137], v[222:223]
	v_pk_fma_f32 v[102:103], v[102:103], v[134:135], v[220:221]
	v_pk_fma_f32 v[100:101], v[100:101], v[132:133], v[226:227]
	v_pk_fma_f32 v[98:99], v[98:99], v[130:131], v[224:225]
	global_store_dwordx4 v[114:115], v[110:113], off sc0 sc1
	global_store_dwordx4 v[114:115], v[106:109], off offset:64 sc0 sc1
	global_store_dwordx4 v[114:115], v[102:105], off offset:512 sc0 sc1
	global_store_dwordx4 v[114:115], v[98:101], off offset:576 sc0 sc1
	global_load_dwordx4 v[110:113], v[118:119], off
	s_nop 0
	global_load_dwordx4 v[106:109], v[118:119], off offset:64
	global_load_dwordx4 v[102:105], v[118:119], off offset:512
	global_load_dwordx4 v[98:101], v[118:119], off offset:576
	v_or_b32_e32 v118, 48, v182
	v_cmp_lt_i32_e32 vcc, s17, v118
	s_and_saveexec_b64 s[38:39], vcc
	s_xor_b64 s[38:39], exec, s[38:39]
	v_add_u32_e32 v0, 0xffff8030, v182
	v_lshlrev_b64 v[114:115], 12, v[0:1]
	v_mov_b32_e32 v119, v1
	v_lshl_add_u64 v[120:121], s[34:35], 0, v[114:115]
	v_lshlrev_b64 v[114:115], 12, v[118:119]
	s_andn2_saveexec_b64 s[38:39], s[38:39]
	v_ashrrev_i32_e32 v119, 31, v118
	v_lshlrev_b64 v[114:115], 12, v[118:119]
	v_lshl_add_u64 v[120:121], s[30:31], 0, v[114:115]
	s_or_b64 exec, exec, s[38:39]
	v_lshl_add_u64 v[146:147], v[120:121], 0, v[180:181]
	global_load_dwordx4 v[118:121], v[146:147], off
	global_load_dwordx4 v[122:125], v[146:147], off offset:64
	global_load_dwordx4 v[126:129], v[146:147], off offset:512
	s_nop 0
	global_load_dwordx4 v[146:149], v[146:147], off offset:576
	s_add_i32 s15, s52, s15
	s_add_i32 s38, s15, 0xffff8000
	v_lshlrev_b64 v[116:117], 12, v[116:117]
	s_lshr_b32 s38, s38, 6
	v_lshl_add_u64 v[116:117], s[24:25], 0, v[116:117]
	s_ashr_i32 s17, s15, 11
	s_add_i32 s38, s38, 16
	v_lshl_add_u64 v[116:117], v[116:117], 0, v[180:181]
	s_waitcnt vmcnt(4)
;     __device__ __forceinline__ void operator()(const f32x4 (&acc)[2][2][4][2], const Unit& u, int wr, int wc, int fr, int fq) const {
;     ...
;                 for (int mm = 0; mm < 2; ++mm) { const int gr = grb + (2 * mp + mm) * 16 + fr;
;                     const float* xr = (gr < MP ? xin_p + (size_t)gr * DM : xin_s + (size_t)(gr - MP) * DM) + col0;
; #pragma unroll
;                     for (int bj = 0; bj < 2; ++bj)
; #pragma unroll
;                         for (int n = 0; n < 2; ++n) xv[mm][bj][n] = *(const f32x4*)(xr + bj * HALF + n * 16); }
; #pragma unroll
;                 for (int mm = 0; mm < 2; ++mm) { const int m = 2 * mp + mm; const int gr = grb + m * 16 + fr; float* orow = out + (size_t)gr * DM + col0;
; #pragma unroll
;                     for (int bj = 0; bj < 2; ++bj)
; #pragma unroll
;                         for (int n = 0; n < 2; ++n) *(f32x4*)(orow + bj * HALF + n * 16) = xv[mm][bj][n] + gv[bj][n] * acc[ai][bj][m][n]; }
	v_pk_fma_f32 v[76:77], v[76:77], v[132:133], v[100:101]
	v_pk_fma_f32 v[74:75], v[74:75], v[130:131], v[98:99]
	s_cmp_lt_i32 s15, 0x8000
	v_or_b32_e32 v98, s15, v169
	s_mov_b32 s15, 0x8000
	v_pk_fma_f32 v[88:89], v[88:89], v[136:137], v[104:105]
	v_pk_fma_f32 v[86:87], v[86:87], v[134:135], v[102:103]
	global_store_dwordx4 v[116:117], v[74:77], off offset:576 sc0 sc1
	v_cmp_gt_i32_e32 vcc, s15, v98
	v_add_u32_e32 v0, 0xffff8000, v98
	v_lshl_add_u64 v[74:75], s[24:25], 0, v[114:115]
	global_store_dwordx4 v[116:117], v[86:89], off offset:512 sc0 sc1
	s_cselect_b32 s17, s17, s38
	v_ashrrev_i32_e32 v99, 31, v98
	v_lshl_add_u64 v[86:87], v[74:75], 0, v[180:181]
	s_mul_hi_i32 s39, s17, 0x6000
	s_mulk_i32 s17, 0x6000
	v_readlane_b32 s28, v255, 25
	v_pk_fma_f32 v[96:97], v[96:97], v[144:145], v[112:113]
	v_pk_fma_f32 v[94:95], v[94:95], v[142:143], v[110:111]
	v_pk_fma_f32 v[92:93], v[92:93], v[140:141], v[108:109]
	v_pk_fma_f32 v[90:91], v[90:91], v[138:139], v[106:107]
	s_add_u32 s38, s28, s17
	v_readlane_b32 s17, v255, 27
	global_store_dwordx4 v[116:117], v[94:97], off sc0 sc1
	global_store_dwordx4 v[116:117], v[90:93], off offset:64 sc0 sc1
	s_addc_u32 s39, s17, s39
	v_or_b32_e32 v102, 16, v98
	s_movk_i32 s15, 0x7fff
	s_waitcnt vmcnt(7)
	v_pk_fma_f32 v[76:77], v[84:85], v[144:145], v[120:121]
	v_pk_fma_f32 v[74:75], v[82:83], v[142:143], v[118:119]
	v_cndmask_b32_e32 v82, v0, v98, vcc
	v_mov_b32_e32 v0, s35
	v_mov_b32_e32 v84, s31
	v_cndmask_b32_e32 v83, 0, v99, vcc
	v_cndmask_b32_e32 v85, v0, v84, vcc
	v_mov_b32_e32 v0, s34
	v_mov_b32_e32 v84, s30
	v_cndmask_b32_e32 v84, v0, v84, vcc
	v_lshlrev_b64 v[82:83], 12, v[82:83]
	global_store_dwordx4 v[86:87], v[74:77], off sc0 sc1
	s_waitcnt vmcnt(6)
	v_pk_fma_f32 v[72:73], v[72:73], v[136:137], v[128:129]
	v_pk_fma_f32 v[70:71], v[70:71], v[134:135], v[126:127]
	v_pk_fma_f32 v[76:77], v[80:81], v[140:141], v[124:125]
	v_pk_fma_f32 v[74:75], v[78:79], v[138:139], v[122:123]
	s_waitcnt vmcnt(5)
	v_pk_fma_f32 v[68:69], v[68:69], v[132:133], v[148:149]
	v_pk_fma_f32 v[66:67], v[66:67], v[130:131], v[146:147]
	v_lshl_add_u64 v[82:83], v[84:85], 0, v[82:83]
	global_store_dwordx4 v[86:87], v[74:77], off offset:64 sc0 sc1
	global_store_dwordx4 v[86:87], v[70:73], off offset:512 sc0 sc1
	global_store_dwordx4 v[86:87], v[66:69], off offset:576 sc0 sc1
	s_cmp_eq_u32 s100, 0
    	s_cbranch_scc1 .Lks6_cont
    	s_waitcnt vmcnt(0)
    	s_andn2_b64 vcc, exec, s[4:5]
    	s_mov_b64 s[4:5], -1
    	s_branch .Lks6_end
;     __device__ __forceinline__ void operator()(const f32x4 (&acc)[2][2][4][2], const Unit& u, int wr, int wc, int fr, int fq) const {
;     ...
;             if (u.part == 0) {
; #pragma unroll
;                 for (int mp = 0; mp < 2; ++mp) {
;                 f32x4 xv[2][2][2];
; #pragma unroll
;                 for (int mm = 0; mm < 2; ++mm) { const int gr = grb + (2 * mp + mm) * 16 + fr;
;                     const float* xr = (gr < MP ? xin_p + (size_t)gr * DM : xin_s + (size_t)(gr - MP) * DM) + col0;
; #pragma unroll
;                     for (int bj = 0; bj < 2; ++bj)
; #pragma unroll
;                         for (int n = 0; n < 2; ++n) xv[mm][bj][n] = *(const f32x4*)(xr + bj * HALF + n * 16); }
; #pragma unroll
;                 for (int mm = 0; mm < 2; ++mm) { const int m = 2 * mp + mm; const int gr = grb + m * 16 + fr; float* orow = out + (size_t)gr * DM + col0;
; #pragma unroll
;                     for (int bj = 0; bj < 2; ++bj)
; #pragma unroll
;                         for (int n = 0; n < 2; ++n) *(f32x4*)(orow + bj * HALF + n * 16) = xv[mm][bj][n] + gv[bj][n] * acc[ai][bj][m][n]; }
    .Lks6_cont:
	v_lshl_add_u64 v[82:83], v[82:83], 0, v[180:181]
	v_cmp_lt_i32_e32 vcc, s15, v102
	v_lshl_add_u64 v[66:67], s[38:39], 0, v[180:181]
	global_load_dwordx4 v[78:81], v[66:67], off
	global_load_dwordx4 v[74:77], v[66:67], off offset:64
	global_load_dwordx4 v[70:73], v[66:67], off offset:512
	s_nop 0
	global_load_dwordx4 v[66:69], v[66:67], off offset:576
	s_nop 0
	global_load_dwordx4 v[94:97], v[82:83], off
	global_load_dwordx4 v[90:93], v[82:83], off offset:64
	global_load_dwordx4 v[86:89], v[82:83], off offset:512
	s_nop 0
	global_load_dwordx4 v[82:85], v[82:83], off offset:576
	s_and_saveexec_b64 s[38:39], vcc
	s_xor_b64 s[38:39], exec, s[38:39]
	v_add_u32_e32 v0, 0xffff8010, v98
	v_lshlrev_b64 v[100:101], 12, v[0:1]
	v_mov_b32_e32 v103, v1
	v_lshl_add_u64 v[104:105], s[34:35], 0, v[100:101]
	v_lshlrev_b64 v[100:101], 12, v[102:103]
	s_andn2_saveexec_b64 s[38:39], s[38:39]
	v_ashrrev_i32_e32 v103, 31, v102
	v_lshlrev_b64 v[100:101], 12, v[102:103]
	v_lshl_add_u64 v[104:105], s[30:31], 0, v[100:101]
	s_or_b64 exec, exec, s[38:39]
	v_lshl_add_u64 v[114:115], v[104:105], 0, v[180:181]
	global_load_dwordx4 v[102:105], v[114:115], off
	global_load_dwordx4 v[106:109], v[114:115], off offset:64
	global_load_dwordx4 v[110:113], v[114:115], off offset:512
	s_nop 0
	global_load_dwordx4 v[114:117], v[114:115], off offset:576
	v_lshlrev_b64 v[118:119], 12, v[98:99]
	s_waitcnt vmcnt(4)
	v_pk_fma_f32 v[82:83], v[50:51], v[66:67], v[82:83]
	v_or_b32_e32 v50, 32, v98
	s_mov_b32 s15, 0x8000
	v_pk_fma_f32 v[54:55], v[54:55], v[70:71], v[86:87]
	v_add_u32_e32 v0, 0xffff8020, v98
	v_lshl_add_u64 v[86:87], s[24:25], 0, v[118:119]
	v_ashrrev_i32_e32 v51, 31, v50
	v_cmp_gt_i32_e32 vcc, s15, v50
	v_pk_fma_f32 v[64:65], v[64:65], v[80:81], v[96:97]
	v_pk_fma_f32 v[62:63], v[62:63], v[78:79], v[94:95]
	v_pk_fma_f32 v[60:61], v[60:61], v[76:77], v[92:93]
	v_pk_fma_f32 v[58:59], v[58:59], v[74:75], v[90:91]
	v_pk_fma_f32 v[56:57], v[56:57], v[72:73], v[88:89]
	v_mov_b32_e32 v90, s35
	v_mov_b32_e32 v91, s31
	v_mov_b32_e32 v92, s34
	v_mov_b32_e32 v93, s30
	v_lshl_add_u64 v[86:87], v[86:87], 0, v[180:181]
	v_cndmask_b32_e32 v89, 0, v51, vcc
	v_cndmask_b32_e32 v88, v0, v50, vcc
	v_pk_fma_f32 v[84:85], v[52:53], v[68:69], v[84:85]
	v_lshl_add_u64 v[52:53], s[24:25], 0, v[100:101]
	v_cndmask_b32_e32 v91, v90, v91, vcc
	v_cndmask_b32_e32 v90, v92, v93, vcc
	global_store_dwordx4 v[86:87], v[62:65], off sc0 sc1
	global_store_dwordx4 v[86:87], v[58:61], off offset:64 sc0 sc1
	global_store_dwordx4 v[86:87], v[54:57], off offset:512 sc0 sc1
	global_store_dwordx4 v[86:87], v[82:85], off offset:576 sc0 sc1
	v_lshl_add_u64 v[52:53], v[52:53], 0, v[180:181]
	v_lshlrev_b64 v[54:55], 12, v[88:89]
	v_lshl_add_u64 v[54:55], v[90:91], 0, v[54:55]
	v_lshl_add_u64 v[54:55], v[54:55], 0, v[180:181]
	s_movk_i32 s15, 0x7fff
	s_waitcnt vmcnt(7)
	v_pk_fma_f32 v[48:49], v[48:49], v[80:81], v[104:105]
	v_pk_fma_f32 v[46:47], v[46:47], v[78:79], v[102:103]
	s_waitcnt vmcnt(6)
	v_pk_fma_f32 v[44:45], v[44:45], v[76:77], v[108:109]
	v_pk_fma_f32 v[42:43], v[42:43], v[74:75], v[106:107]
	s_waitcnt vmcnt(5)
	v_pk_fma_f32 v[40:41], v[40:41], v[72:73], v[112:113]
	v_pk_fma_f32 v[38:39], v[38:39], v[70:71], v[110:111]
	s_waitcnt vmcnt(4)
	v_pk_fma_f32 v[36:37], v[36:37], v[68:69], v[116:117]
	v_pk_fma_f32 v[34:35], v[34:35], v[66:67], v[114:115]
	global_store_dwordx4 v[52:53], v[46:49], off sc0 sc1
	global_store_dwordx4 v[52:53], v[42:45], off offset:64 sc0 sc1
	global_store_dwordx4 v[52:53], v[38:41], off offset:512 sc0 sc1
	global_store_dwordx4 v[52:53], v[34:37], off offset:576 sc0 sc1
	global_load_dwordx4 v[46:49], v[54:55], off
	s_nop 0
	global_load_dwordx4 v[42:45], v[54:55], off offset:64
	global_load_dwordx4 v[38:41], v[54:55], off offset:512
	global_load_dwordx4 v[34:37], v[54:55], off offset:576
	v_or_b32_e32 v54, 48, v98
	v_cmp_lt_i32_e32 vcc, s15, v54
	s_and_saveexec_b64 s[38:39], vcc
	s_xor_b64 s[38:39], exec, s[38:39]
	v_add_u32_e32 v0, 0xffff8030, v98
	v_lshlrev_b64 v[52:53], 12, v[0:1]
	v_mov_b32_e32 v55, v1
	v_lshl_add_u64 v[56:57], s[34:35], 0, v[52:53]
	v_lshlrev_b64 v[52:53], 12, v[54:55]
	s_andn2_saveexec_b64 s[38:39], s[38:39]
	v_ashrrev_i32_e32 v55, 31, v54
	v_lshlrev_b64 v[52:53], 12, v[54:55]
	v_lshl_add_u64 v[56:57], s[30:31], 0, v[52:53]
	s_or_b64 exec, exec, s[38:39]
	v_lshl_add_u64 v[82:83], v[56:57], 0, v[180:181]
	global_load_dwordx4 v[54:57], v[82:83], off
	global_load_dwordx4 v[58:61], v[82:83], off offset:64
	global_load_dwordx4 v[62:65], v[82:83], off offset:512
	s_nop 0
	global_load_dwordx4 v[82:85], v[82:83], off offset:576
	v_lshlrev_b64 v[50:51], 12, v[50:51]
	s_waitcnt vmcnt(4)
	v_pk_fma_f32 v[20:21], v[20:21], v[68:69], v[36:37]
	v_pk_fma_f32 v[18:19], v[18:19], v[66:67], v[34:35]
	v_lshl_add_u64 v[34:35], s[24:25], 0, v[52:53]
	v_lshl_add_u64 v[36:37], s[24:25], 0, v[50:51]
	v_pk_fma_f32 v[32:33], v[32:33], v[80:81], v[48:49]
	v_pk_fma_f32 v[30:31], v[30:31], v[78:79], v[46:47]
	v_lshl_add_u64 v[34:35], v[34:35], 0, v[180:181]
	v_lshl_add_u64 v[36:37], v[36:37], 0, v[180:181]
	s_andn2_b64 vcc, exec, s[4:5]
	s_mov_b64 s[4:5], -1
	v_pk_fma_f32 v[28:29], v[28:29], v[76:77], v[44:45]
	v_pk_fma_f32 v[26:27], v[26:27], v[74:75], v[42:43]
	v_pk_fma_f32 v[24:25], v[24:25], v[72:73], v[40:41]
	v_pk_fma_f32 v[22:23], v[22:23], v[70:71], v[38:39]
	global_store_dwordx4 v[36:37], v[30:33], off sc0 sc1
	global_store_dwordx4 v[36:37], v[26:29], off offset:64 sc0 sc1
	global_store_dwordx4 v[36:37], v[22:25], off offset:512 sc0 sc1
	global_store_dwordx4 v[36:37], v[18:21], off offset:576 sc0 sc1
	s_waitcnt vmcnt(7)
	v_pk_fma_f32 v[16:17], v[16:17], v[80:81], v[56:57]
	v_pk_fma_f32 v[14:15], v[14:15], v[78:79], v[54:55]
	s_waitcnt vmcnt(6)
	v_pk_fma_f32 v[12:13], v[12:13], v[76:77], v[60:61]
	v_pk_fma_f32 v[10:11], v[10:11], v[74:75], v[58:59]
	s_waitcnt vmcnt(5)
	v_pk_fma_f32 v[8:9], v[8:9], v[72:73], v[64:65]
	v_pk_fma_f32 v[6:7], v[6:7], v[70:71], v[62:63]
	s_waitcnt vmcnt(4)
	v_pk_fma_f32 v[4:5], v[4:5], v[68:69], v[84:85]
	v_pk_fma_f32 v[2:3], v[2:3], v[66:67], v[82:83]
	global_store_dwordx4 v[34:35], v[14:17], off sc0 sc1
	global_store_dwordx4 v[34:35], v[10:13], off offset:64 sc0 sc1
	global_store_dwordx4 v[34:35], v[6:9], off offset:512 sc0 sc1
	global_store_dwordx4 v[34:35], v[2:5], off offset:576 sc0 sc1
	s_cmp_lg_u32 s53, 1
	s_cbranch_scc1 .Lp7e_nosig
	v_readlane_b32 s28, v255, 31
	s_cmp_eq_u32 s28, 0
	s_cbranch_scc1 .Lp7e_nosig
	s_waitcnt vmcnt(0)
	s_barrier
	v_readfirstlane_b32 s28, v166
	s_nop 0
	s_cmp_lt_u32 s28, 64
	s_cbranch_scc0 .Lp7e_nosig
	s_add_u32 s38, s26, 0x1d780000
	s_addc_u32 s39, s27, 0
	v_mov_b32_e32 v34, 0x3800
	v_mov_b32_e32 v35, 1
	s_mov_b64 s[42:43], exec
	s_mov_b64 exec, 1
	global_atomic_add v34, v35, s[38:39] sc1
	s_mov_b64 exec, s[42:43]
.Lp7e_nosig:
.Lks6_end:
	s_cbranch_vccnz .LBB0_777
	s_andn2_b64 vcc, exec, s[6:7]
	s_cbranch_vccnz .LBB0_776
	s_barrier
	s_branch .LBB0_776

; __device__ __forceinline__ void norm_mod_rows(const float* __restrict__ xp, const float* __restrict__ xs, const float* __restrict__ gvec, const float* __restrict__ mod, int ch_shift, int ch_scale, ...
;     for (int r0 = gw; r0 < nrows; r0 += 2 * NGW) {
;         const int r1 = r0 + NGW; const bool two = r1 < nrows;
;         const int gr0 = row_base + r0, gr1 = row_base + (two ? r1 : r0);
;         const float* xrow0 = gr0 < MP ? xp + (size_t)gr0 * DM : xs + (size_t)(gr0 - MP) * DM;
;         const float* xrow1 = gr1 < MP ? xp + (size_t)gr1 * DM : xs + (size_t)(gr1 - MP) * DM;
;         f32x4 v0[4], v1[4]; float s0 = 0.f, s1 = 0.f;
; #pragma unroll
;         for (int j = 0; j < 4; ++j) { v0[j] = ((const f32x4*)xrow0)[lane + 64 * j]; v1[j] = ((const f32x4*)xrow1)[lane + 64 * j]; }
; #pragma unroll
;         for (int j = 0; j < 4; ++j) { s0 += (v0[j][0] * v0[j][0] + v0[j][1] * v0[j][1]) + (v0[j][2] * v0[j][2] + v0[j][3] * v0[j][3]);
;                                       s1 += (v1[j][0] * v1[j][0] + v1[j][1] * v1[j][1]) + (v1[j][2] * v1[j][2] + v1[j][3] * v1[j][3]); }
;         const float rstd0 = rsqrtf(wave_sum(s0) * (1.f / DM) + EPS), rstd1 = rsqrtf(wave_sum(s1) * (1.f / DM) + EPS);
; #pragma unroll
;         for (int q = 0; q < 2; ++q) {
;             if (q == 1 && !two) break;
;             const int gr = q ? gr1 : gr0, r = q ? r1 : r0; const float rstd = q ? rstd1 : rstd0;
;             const int seq = gr < MP ? (gr >> 11) : NPB + ((gr - MP) >> 6);
;             const float* mrow = mod + (size_t)seq * (6 * DM);
;             u32x2* o8 = (u32x2*)(H + (size_t)r * DM);
;             f32x4 gq[4], scq[4], shq[4];
; #pragma unroll
;             for (int j = 0; j < 4; ++j) { const int ci = lane + 64 * j;
;                 gq[j] = ((const f32x4*)gvec)[ci]; scq[j] = ((const f32x4*)(mrow + ch_scale * DM))[ci]; shq[j] = ((const f32x4*)(mrow + ch_shift * DM))[ci]; }
.LBB0_804:
	v_readlane_b32 s3, v255, 31
	v_readlane_b32 s4, v252, 2
	s_cmp_eq_u32 s3, 0
	s_cbranch_scc1 .Lp7e_skip
	s_cmp_lt_u32 s4, 0x8000
	s_cbranch_scc1 .Lp7e_skip
	v_readfirstlane_b32 s3, v166
	s_nop 0
	s_cmp_lt_u32 s3, 64
	s_cbranch_scc0 .Lp7e_wb
	v_readlane_b32 s5, v255, 5
	s_lshr_b32 s5, s5, 12
	s_add_i32 s5, s5, 1
	s_lshl_b32 s5, s5, 8
	s_add_u32 s8, s26, 0x1d780000
	s_addc_u32 s9, s27, 0
	v_mov_b32_e32 v62, 0x3800
	s_mov_b32 s28, 0
.Lp7e_poll:
	global_load_dword v63, v62, s[8:9] sc0 sc1
	s_waitcnt vmcnt(0)
	v_readfirstlane_b32 s29, v63
	s_add_i32 s28, s28, 1
	s_cmp_ge_u32 s29, s5
	s_cbranch_scc1 .Lp7e_got
	s_sleep 1
	s_cmp_lt_u32 s28, 0x8000
	s_cbranch_scc1 .Lp7e_poll
.Lp7e_got:
	buffer_inv sc1
	s_waitcnt vmcnt(0)
.Lp7e_wb:
	s_barrier
	v_readlane_b32 s48, v255, 0
	v_readlane_b32 s49, v255, 1
	v_and_b32_e32 v216, 63, v166
	v_lshlrev_b32_e32 v80, 4, v216
	v_readlane_b32 s40, v255, 5
	v_readlane_b32 s41, v255, 6
	v_readlane_b32 s42, v252, 13
	v_readlane_b32 s43, v252, 14
	s_add_u32 s40, s42, s40
	s_addc_u32 s41, s43, s41
	s_nop 4
	global_load_dwordx4 v[96:99], v80, s[40:41]
	global_load_dwordx4 v[100:103], v80, s[40:41] offset:1024
	global_load_dwordx4 v[104:107], v80, s[40:41] offset:2048
	global_load_dwordx4 v[108:111], v80, s[40:41] offset:3072
	v_add_u32_e32 v81, 0x1000, v80
	v_add_u32_e32 v82, 0x3000, v80
	v_add_u32_e32 v83, 0x4000, v80
	v_lshlrev_b32_e32 v0, 3, v216
	v_readlane_b32 s3, v254, 25
	s_movk_i32 s5, 0x600
	s_add_i32 s3, s3, 0xfffffe00
	s_movk_i32 s4, 0x1400
	s_movk_i32 s8, 0x4000
	s_cmp_ge_i32 s3, s4
	s_cbranch_scc1 .Lp7e_skip
.Lnorm_loop_p7e:
	s_lshr_b32 s46, s3, 10
	s_and_b32 s9, s3, 0x3ff
	s_lshl_b32 s9, s9, 1
	s_lshl_b32 s28, s46, 12
	s_add_i32 s28, s28, 0xfffffc00
	s_cmp_eq_u32 s46, 0
	s_cselect_b32 s28, 0, s28
	s_add_i32 s9, s9, s28
	s_add_i32 s28, s9, s8
	s_lshl_b32 s46, s9, 11
	s_add_u32 s44, s12, s46
	s_addc_u32 s45, s13, 0
	s_add_i32 s9, s28, 0xffff8000
	s_ashr_i32 s46, s28, 11
	s_lshr_b32 s42, s9, 6
	s_add_i32 s42, s42, 16
	s_cmp_lt_i32 s28, 0x8000
	s_cselect_b32 s40, s24, s48
	s_cselect_b32 s41, s25, s49
	s_cselect_b32 s9, s28, s9
	s_cselect_b32 s46, s46, s42
	s_lshl_b32 s9, s9, 12
	s_add_u32 s40, s40, s9
	s_addc_u32 s41, s41, 0
	s_mul_i32 s46, s46, 0x6000
	v_readlane_b32 s42, v255, 24
	v_readlane_b32 s43, v255, 26
	s_add_u32 s42, s42, s46
	s_addc_u32 s43, s43, 0
	global_load_dwordx4 v[216:219], v80, s[40:41]
	global_load_dwordx4 v[220:223], v80, s[40:41] offset:1024
	global_load_dwordx4 v[224:227], v80, s[40:41] offset:2048
	global_load_dwordx4 v[228:231], v80, s[40:41] offset:3072
	global_load_dwordx4 v[232:235], v81, s[40:41]
	global_load_dwordx4 v[236:239], v81, s[40:41] offset:1024
	global_load_dwordx4 v[240:243], v81, s[40:41] offset:2048
	global_load_dwordx4 v[244:247], v81, s[40:41] offset:3072
	global_load_dwordx4 v[62:65], v83, s[42:43]
	global_load_dwordx4 v[66:69], v83, s[42:43] offset:1024
	global_load_dwordx4 v[70:73], v83, s[42:43] offset:2048
	global_load_dwordx4 v[74:77], v83, s[42:43] offset:3072
	global_load_dwordx4 v[176:179], v82, s[42:43]
	global_load_dwordx4 v[180:183], v82, s[42:43] offset:1024
	global_load_dwordx4 v[184:187], v82, s[42:43] offset:2048
	global_load_dwordx4 v[188:191], v82, s[42:43] offset:3072
	s_waitcnt vmcnt(15)
	v_pk_mul_f32 v[78:79], v[216:217], v[216:217]
	v_pk_fma_f32 v[78:79], v[218:219], v[218:219], v[78:79]
	s_waitcnt vmcnt(14)
	v_pk_fma_f32 v[78:79], v[220:221], v[220:221], v[78:79]
	v_pk_fma_f32 v[78:79], v[222:223], v[222:223], v[78:79]
	s_waitcnt vmcnt(13)
	v_pk_fma_f32 v[78:79], v[224:225], v[224:225], v[78:79]
	v_pk_fma_f32 v[78:79], v[226:227], v[226:227], v[78:79]
	s_waitcnt vmcnt(12)
	v_pk_fma_f32 v[78:79], v[228:229], v[228:229], v[78:79]
	v_pk_fma_f32 v[78:79], v[230:231], v[230:231], v[78:79]
	s_waitcnt vmcnt(11)
	v_pk_mul_f32 v[120:121], v[232:233], v[232:233]
	v_pk_fma_f32 v[120:121], v[234:235], v[234:235], v[120:121]
	s_waitcnt vmcnt(10)
	v_pk_fma_f32 v[120:121], v[236:237], v[236:237], v[120:121]
	v_pk_fma_f32 v[120:121], v[238:239], v[238:239], v[120:121]
	s_waitcnt vmcnt(9)
	v_pk_fma_f32 v[120:121], v[240:241], v[240:241], v[120:121]
	v_pk_fma_f32 v[120:121], v[242:243], v[242:243], v[120:121]
	s_waitcnt vmcnt(8)
	v_pk_fma_f32 v[120:121], v[244:245], v[244:245], v[120:121]
	v_pk_fma_f32 v[120:121], v[246:247], v[246:247], v[120:121]
	s_nop 0
	v_add_f32_e32 v78, v78, v79
	v_add_f32_e32 v120, v120, v121
	s_nop 1
	v_add_f32_dpp v78, v78, v78 quad_perm:[1,0,3,2] row_mask:0xf bank_mask:0xf bound_ctrl:1
	v_add_f32_dpp v120, v120, v120 quad_perm:[1,0,3,2] row_mask:0xf bank_mask:0xf bound_ctrl:1
	s_nop 1
	v_add_f32_dpp v78, v78, v78 quad_perm:[2,3,0,1] row_mask:0xf bank_mask:0xf bound_ctrl:1
	v_add_f32_dpp v120, v120, v120 quad_perm:[2,3,0,1] row_mask:0xf bank_mask:0xf bound_ctrl:1
	s_nop 1
	v_add_f32_dpp v78, v78, v78 row_half_mirror row_mask:0xf bank_mask:0xf bound_ctrl:1
	v_add_f32_dpp v120, v120, v120 row_half_mirror row_mask:0xf bank_mask:0xf bound_ctrl:1
	s_nop 1
	v_add_f32_dpp v78, v78, v78 row_mirror row_mask:0xf bank_mask:0xf bound_ctrl:1
	v_add_f32_dpp v120, v120, v120 row_mirror row_mask:0xf bank_mask:0xf bound_ctrl:1
	s_nop 1
	v_add_f32_dpp v78, v78, v78 row_bcast:15 row_mask:0xa bank_mask:0xf
	v_add_f32_dpp v120, v120, v120 row_bcast:15 row_mask:0xa bank_mask:0xf
	s_nop 1
	v_add_f32_dpp v78, v78, v78 row_bcast:31 row_mask:0xc bank_mask:0xf
	v_add_f32_dpp v120, v120, v120 row_bcast:31 row_mask:0xc bank_mask:0xf
	s_nop 1
	v_readlane_b32 s9, v78, 63
	v_readlane_b32 s28, v120, 63
	s_nop 2
	v_mov_b32_e32 v122, s9
	v_mov_b32_e32 v124, s28
	v_fmamk_f32 v122, v122, 0x3a800000, v167
	v_fmamk_f32 v124, v124, 0x3a800000, v167
	v_rsq_f32_e32 v122, v122
	v_rsq_f32_e32 v124, v124
	s_waitcnt vmcnt(4)
; __device__ __forceinline__ unsigned pk2(float lo, float hi) { unsigned r; asm("v_cvt_pk_bf16_f32 %0, %1, %2" : "=v"(r) : "v"(lo), "v"(hi)); return r; }
; __device__ __forceinline__ void norm_mod_rows(const float* __restrict__ xp, const float* __restrict__ xs, const float* __restrict__ gvec, const float* __restrict__ mod, int ch_shift, int ch_scale, ...
;     ...
; #pragma unroll
;             for (int j = 0; j < 4; ++j) { const int ci = lane + 64 * j;
;                 const f32x4 y = ((q ? v1[j] : v0[j]) * rstd) * gq[j] * (scq[j] + 1.f) + shq[j];
;                 u32x2 w; w.x = pk2(y[0], y[1]); w.y = pk2(y[2], y[3]); o8[ci] = w; }
;         }
	v_pk_add_f32 v[62:63], v[62:63], 1.0 op_sel_hi:[1,0]
	v_pk_add_f32 v[64:65], v[64:65], 1.0 op_sel_hi:[1,0]
	v_pk_add_f32 v[66:67], v[66:67], 1.0 op_sel_hi:[1,0]
	v_pk_add_f32 v[68:69], v[68:69], 1.0 op_sel_hi:[1,0]
	v_pk_add_f32 v[70:71], v[70:71], 1.0 op_sel_hi:[1,0]
	v_pk_add_f32 v[72:73], v[72:73], 1.0 op_sel_hi:[1,0]
	v_pk_add_f32 v[74:75], v[74:75], 1.0 op_sel_hi:[1,0]
	v_pk_add_f32 v[76:77], v[76:77], 1.0 op_sel_hi:[1,0]
	s_waitcnt vmcnt(0)
	v_pk_mul_f32 v[216:217], v[216:217], v[122:123] op_sel_hi:[1,0]
	v_pk_mul_f32 v[218:219], v[218:219], v[122:123] op_sel_hi:[1,0]
	v_pk_mul_f32 v[220:221], v[220:221], v[122:123] op_sel_hi:[1,0]
	v_pk_mul_f32 v[222:223], v[222:223], v[122:123] op_sel_hi:[1,0]
	v_pk_mul_f32 v[224:225], v[224:225], v[122:123] op_sel_hi:[1,0]
	v_pk_mul_f32 v[226:227], v[226:227], v[122:123] op_sel_hi:[1,0]
	v_pk_mul_f32 v[228:229], v[228:229], v[122:123] op_sel_hi:[1,0]
	v_pk_mul_f32 v[230:231], v[230:231], v[122:123] op_sel_hi:[1,0]
	v_pk_mul_f32 v[216:217], v[96:97], v[216:217]
	v_pk_mul_f32 v[218:219], v[98:99], v[218:219]
	v_pk_mul_f32 v[220:221], v[100:101], v[220:221]
	v_pk_mul_f32 v[222:223], v[102:103], v[222:223]
	v_pk_mul_f32 v[224:225], v[104:105], v[224:225]
	v_pk_mul_f32 v[226:227], v[106:107], v[226:227]
	v_pk_mul_f32 v[228:229], v[108:109], v[228:229]
	v_pk_mul_f32 v[230:231], v[110:111], v[230:231]
	v_pk_fma_f32 v[216:217], v[62:63], v[216:217], v[176:177]
	v_pk_fma_f32 v[218:219], v[64:65], v[218:219], v[178:179]
	v_pk_fma_f32 v[220:221], v[66:67], v[220:221], v[180:181]
	v_pk_fma_f32 v[222:223], v[68:69], v[222:223], v[182:183]
	v_pk_fma_f32 v[224:225], v[70:71], v[224:225], v[184:185]
	v_pk_fma_f32 v[226:227], v[72:73], v[226:227], v[186:187]
	v_pk_fma_f32 v[228:229], v[74:75], v[228:229], v[188:189]
	v_pk_fma_f32 v[230:231], v[76:77], v[230:231], v[190:191]
	v_cvt_pk_bf16_f32 v216, v216, v217
	v_cvt_pk_bf16_f32 v217, v218, v219
	v_cvt_pk_bf16_f32 v220, v220, v221
	v_cvt_pk_bf16_f32 v221, v222, v223
	v_cvt_pk_bf16_f32 v224, v224, v225
	v_cvt_pk_bf16_f32 v225, v226, v227
	v_cvt_pk_bf16_f32 v228, v228, v229
	v_cvt_pk_bf16_f32 v229, v230, v231
	global_store_dwordx2 v0, v[216:217], s[44:45]
	global_store_dwordx2 v0, v[220:221], s[44:45] offset:512
	global_store_dwordx2 v0, v[224:225], s[44:45] offset:1024
	global_store_dwordx2 v0, v[228:229], s[44:45] offset:1536
	v_pk_mul_f32 v[232:233], v[232:233], v[124:125] op_sel_hi:[1,0]
	v_pk_mul_f32 v[234:235], v[234:235], v[124:125] op_sel_hi:[1,0]
	v_pk_mul_f32 v[236:237], v[236:237], v[124:125] op_sel_hi:[1,0]
	v_pk_mul_f32 v[238:239], v[238:239], v[124:125] op_sel_hi:[1,0]
	v_pk_mul_f32 v[240:241], v[240:241], v[124:125] op_sel_hi:[1,0]
	v_pk_mul_f32 v[242:243], v[242:243], v[124:125] op_sel_hi:[1,0]
	v_pk_mul_f32 v[244:245], v[244:245], v[124:125] op_sel_hi:[1,0]
	v_pk_mul_f32 v[246:247], v[246:247], v[124:125] op_sel_hi:[1,0]
	v_pk_mul_f32 v[232:233], v[96:97], v[232:233]
	v_pk_mul_f32 v[234:235], v[98:99], v[234:235]
	v_pk_mul_f32 v[236:237], v[100:101], v[236:237]
	v_pk_mul_f32 v[238:239], v[102:103], v[238:239]
	v_pk_mul_f32 v[240:241], v[104:105], v[240:241]
	v_pk_mul_f32 v[242:243], v[106:107], v[242:243]
	v_pk_mul_f32 v[244:245], v[108:109], v[244:245]
	v_pk_mul_f32 v[246:247], v[110:111], v[246:247]
	v_pk_fma_f32 v[232:233], v[62:63], v[232:233], v[176:177]
	v_pk_fma_f32 v[234:235], v[64:65], v[234:235], v[178:179]
	v_pk_fma_f32 v[236:237], v[66:67], v[236:237], v[180:181]
	v_pk_fma_f32 v[238:239], v[68:69], v[238:239], v[182:183]
	v_pk_fma_f32 v[240:241], v[70:71], v[240:241], v[184:185]
	v_pk_fma_f32 v[242:243], v[72:73], v[242:243], v[186:187]
	v_pk_fma_f32 v[244:245], v[74:75], v[244:245], v[188:189]
	v_pk_fma_f32 v[246:247], v[76:77], v[246:247], v[190:191]
	v_cvt_pk_bf16_f32 v232, v232, v233
	v_cvt_pk_bf16_f32 v233, v234, v235
	v_cvt_pk_bf16_f32 v236, v236, v237
	v_cvt_pk_bf16_f32 v237, v238, v239
	v_cvt_pk_bf16_f32 v240, v240, v241
	v_cvt_pk_bf16_f32 v241, v242, v243
	v_cvt_pk_bf16_f32 v244, v244, v245
	v_cvt_pk_bf16_f32 v245, v246, v247
	global_store_dwordx2 v0, v[232:233], s[44:45] offset:2048
	global_store_dwordx2 v0, v[236:237], s[44:45] offset:2560
	global_store_dwordx2 v0, v[240:241], s[44:45] offset:3072
	global_store_dwordx2 v0, v[244:245], s[44:45] offset:3584
	s_add_i32 s3, s3, s5
	s_cmp_lt_i32 s3, s4
	s_cbranch_scc1 .Lnorm_loop_p7e

; __device__ __forceinline__ void norm_mod_rows(const float* __restrict__ xp, const float* __restrict__ xs, const float* __restrict__ gvec, const float* __restrict__ mod, int ch_shift, int ch_scale, ...
;     for (int r0 = gw; r0 < nrows; r0 += 2 * NGW) {
;         const int r1 = r0 + NGW; const bool two = r1 < nrows;
;         const int gr0 = row_base + r0, gr1 = row_base + (two ? r1 : r0);
;         const float* xrow0 = gr0 < MP ? xp + (size_t)gr0 * DM : xs + (size_t)(gr0 - MP) * DM;
;         const float* xrow1 = gr1 < MP ? xp + (size_t)gr1 * DM : xs + (size_t)(gr1 - MP) * DM;
;         f32x4 v0[4], v1[4]; float s0 = 0.f, s1 = 0.f;
; #pragma unroll
;         for (int j = 0; j < 4; ++j) { v0[j] = ((const f32x4*)xrow0)[lane + 64 * j]; v1[j] = ((const f32x4*)xrow1)[lane + 64 * j]; }
; #pragma unroll
;         for (int j = 0; j < 4; ++j) { s0 += (v0[j][0] * v0[j][0] + v0[j][1] * v0[j][1]) + (v0[j][2] * v0[j][2] + v0[j][3] * v0[j][3]);
;                                       s1 += (v1[j][0] * v1[j][0] + v1[j][1] * v1[j][1]) + (v1[j][2] * v1[j][2] + v1[j][3] * v1[j][3]); }
;         const float rstd0 = rsqrtf(wave_sum(s0) * (1.f / DM) + EPS), rstd1 = rsqrtf(wave_sum(s1) * (1.f / DM) + EPS);
; #pragma unroll
;         for (int q = 0; q < 2; ++q) {
;             if (q == 1 && !two) break;
;             const int gr = q ? gr1 : gr0, r = q ? r1 : r0; const float rstd = q ? rstd1 : rstd0;
;             const int seq = gr < MP ? (gr >> 11) : NPB + ((gr - MP) >> 6);
;             const float* mrow = mod + (size_t)seq * (6 * DM);
.LBB0_855:
	v_readlane_b32 s2, v253, 62
	v_readlane_b32 s3, v253, 63
	v_readlane_b32 s34, v255, 0
	v_mov_b32_e32 v0, v166
	s_andn2_b64 vcc, exec, s[2:3]
	v_readlane_b32 s35, v255, 1
	s_cbranch_vccnz .LBB0_860
	v_and_b32_e32 v18, 63, v166
	v_lshlrev_b32_e32 v85, 4, v18
	v_readlane_b32 s14, v255, 5
	v_readlane_b32 s15, v255, 6
	v_readlane_b32 s16, v252, 13
	v_readlane_b32 s17, v252, 14
	s_add_u32 s14, s16, s14
	s_addc_u32 s15, s17, s15
	s_nop 4
	global_load_dwordx4 v[2:5], v85, s[14:15]
	global_load_dwordx4 v[6:9], v85, s[14:15] offset:1024
	global_load_dwordx4 v[10:13], v85, s[14:15] offset:2048
	global_load_dwordx4 v[14:17], v85, s[14:15] offset:3072
	v_add_u32_e32 v86, 0x1000, v85
	v_add_u32_e32 v87, 0x3000, v85
	v_add_u32_e32 v88, 0x4000, v85
	v_lshlrev_b32_e32 v0, 3, v18
	v_readlane_b32 s3, v254, 25
	v_readlane_b32 s5, v252, 4
	s_movk_i32 s4, 0x1000
	s_movk_i32 s8, 0x4000
	s_cmp_ge_i32 s3, s4
	s_cbranch_scc1 .LBB0_860
.Lnorm_loop_p7:
	s_lshr_b32 s22, s3, 9
	s_and_b32 s9, s3, 0x1ff
	s_lshl_b32 s9, s9, 1
	s_lshr_b32 s10, s22, 1
	s_lshl_b32 s10, s10, 12
	s_add_i32 s9, s9, s10
	s_and_b32 s10, s22, 1
	s_mul_i32 s10, s10, 0xc00
	s_add_i32 s9, s9, s10
	s_addk_i32 s9, 0x800
	s_add_i32 s10, s9, s8
	s_lshl_b32 s22, s9, 11
	s_add_u32 s20, s12, s22
	s_addc_u32 s21, s13, 0
	s_add_i32 s9, s10, 0xffff8000
	s_ashr_i32 s22, s10, 11
	s_lshr_b32 s16, s9, 6
	s_add_i32 s16, s16, 16
	s_cmp_lt_i32 s10, 0x8000
	s_cselect_b32 s14, s24, s34
	s_cselect_b32 s15, s25, s35
	s_cselect_b32 s9, s10, s9
	s_cselect_b32 s22, s22, s16
	s_lshl_b32 s9, s9, 12
	s_add_u32 s14, s14, s9
	s_addc_u32 s15, s15, 0
	s_mul_i32 s22, s22, 0x6000
	v_readlane_b32 s16, v255, 24
	v_readlane_b32 s17, v255, 26
	s_add_u32 s16, s16, s22
	s_addc_u32 s17, s17, 0
	global_load_dwordx4 v[18:21], v85, s[14:15]
	global_load_dwordx4 v[22:25], v85, s[14:15] offset:1024
	global_load_dwordx4 v[26:29], v85, s[14:15] offset:2048
	global_load_dwordx4 v[30:33], v85, s[14:15] offset:3072
	global_load_dwordx4 v[34:37], v86, s[14:15]
	global_load_dwordx4 v[38:41], v86, s[14:15] offset:1024
	global_load_dwordx4 v[42:45], v86, s[14:15] offset:2048
	global_load_dwordx4 v[46:49], v86, s[14:15] offset:3072
	global_load_dwordx4 v[50:53], v88, s[16:17]
	global_load_dwordx4 v[54:57], v88, s[16:17] offset:1024
	global_load_dwordx4 v[58:61], v88, s[16:17] offset:2048
	global_load_dwordx4 v[62:65], v88, s[16:17] offset:3072
	global_load_dwordx4 v[66:69], v87, s[16:17]
	global_load_dwordx4 v[70:73], v87, s[16:17] offset:1024
	global_load_dwordx4 v[74:77], v87, s[16:17] offset:2048
	global_load_dwordx4 v[78:81], v87, s[16:17] offset:3072
	s_waitcnt vmcnt(15)
	v_pk_mul_f32 v[82:83], v[18:19], v[18:19]
	v_pk_fma_f32 v[82:83], v[20:21], v[20:21], v[82:83]
	s_waitcnt vmcnt(14)
	v_pk_fma_f32 v[82:83], v[22:23], v[22:23], v[82:83]
	v_pk_fma_f32 v[82:83], v[24:25], v[24:25], v[82:83]
	s_waitcnt vmcnt(13)
	v_pk_fma_f32 v[82:83], v[26:27], v[26:27], v[82:83]
	v_pk_fma_f32 v[82:83], v[28:29], v[28:29], v[82:83]
	s_waitcnt vmcnt(12)
	v_pk_fma_f32 v[82:83], v[30:31], v[30:31], v[82:83]
	v_pk_fma_f32 v[82:83], v[32:33], v[32:33], v[82:83]
	s_waitcnt vmcnt(11)
	v_pk_mul_f32 v[90:91], v[34:35], v[34:35]
	v_pk_fma_f32 v[90:91], v[36:37], v[36:37], v[90:91]
	s_waitcnt vmcnt(10)
	v_pk_fma_f32 v[90:91], v[38:39], v[38:39], v[90:91]
	v_pk_fma_f32 v[90:91], v[40:41], v[40:41], v[90:91]
	s_waitcnt vmcnt(9)
	v_pk_fma_f32 v[90:91], v[42:43], v[42:43], v[90:91]
	v_pk_fma_f32 v[90:91], v[44:45], v[44:45], v[90:91]
	s_waitcnt vmcnt(8)
	v_pk_fma_f32 v[90:91], v[46:47], v[46:47], v[90:91]
	v_pk_fma_f32 v[90:91], v[48:49], v[48:49], v[90:91]
	s_nop 0
	v_add_f32_e32 v82, v82, v83
	v_add_f32_e32 v90, v90, v91
	s_nop 1
	v_add_f32_dpp v82, v82, v82 quad_perm:[1,0,3,2] row_mask:0xf bank_mask:0xf bound_ctrl:1
	v_add_f32_dpp v90, v90, v90 quad_perm:[1,0,3,2] row_mask:0xf bank_mask:0xf bound_ctrl:1
	s_nop 1
	v_add_f32_dpp v82, v82, v82 quad_perm:[2,3,0,1] row_mask:0xf bank_mask:0xf bound_ctrl:1
	v_add_f32_dpp v90, v90, v90 quad_perm:[2,3,0,1] row_mask:0xf bank_mask:0xf bound_ctrl:1
	s_nop 1
	v_add_f32_dpp v82, v82, v82 row_half_mirror row_mask:0xf bank_mask:0xf bound_ctrl:1
	v_add_f32_dpp v90, v90, v90 row_half_mirror row_mask:0xf bank_mask:0xf bound_ctrl:1
	s_nop 1
	v_add_f32_dpp v82, v82, v82 row_mirror row_mask:0xf bank_mask:0xf bound_ctrl:1
	v_add_f32_dpp v90, v90, v90 row_mirror row_mask:0xf bank_mask:0xf bound_ctrl:1
	s_nop 1
	v_add_f32_dpp v82, v82, v82 row_bcast:15 row_mask:0xa bank_mask:0xf
	v_add_f32_dpp v90, v90, v90 row_bcast:15 row_mask:0xa bank_mask:0xf
	s_nop 1
	v_add_f32_dpp v82, v82, v82 row_bcast:31 row_mask:0xc bank_mask:0xf
	v_add_f32_dpp v90, v90, v90 row_bcast:31 row_mask:0xc bank_mask:0xf
	s_nop 1
	v_readlane_b32 s9, v82, 63
	v_readlane_b32 s10, v90, 63
	s_nop 2
	v_mov_b32_e32 v92, s9
	v_mov_b32_e32 v94, s10
	v_fmamk_f32 v92, v92, 0x3a800000, v167
	v_fmamk_f32 v94, v94, 0x3a800000, v167
	v_rsq_f32_e32 v92, v92
	v_rsq_f32_e32 v94, v94
	s_waitcnt vmcnt(4)
; __device__ __forceinline__ unsigned pk2(float lo, float hi) { unsigned r; asm("v_cvt_pk_bf16_f32 %0, %1, %2" : "=v"(r) : "v"(lo), "v"(hi)); return r; }
; __device__ __forceinline__ void norm_mod_rows(const float* __restrict__ xp, const float* __restrict__ xs, const float* __restrict__ gvec, const float* __restrict__ mod, int ch_shift, int ch_scale, ...
;     ...
;             f32x4 gq[4], scq[4], shq[4];
; #pragma unroll
;             for (int j = 0; j < 4; ++j) { const int ci = lane + 64 * j;
;                 gq[j] = ((const f32x4*)gvec)[ci]; scq[j] = ((const f32x4*)(mrow + ch_scale * DM))[ci]; shq[j] = ((const f32x4*)(mrow + ch_shift * DM))[ci]; }
; #pragma unroll
;             for (int j = 0; j < 4; ++j) { const int ci = lane + 64 * j;
;                 const f32x4 y = ((q ? v1[j] : v0[j]) * rstd) * gq[j] * (scq[j] + 1.f) + shq[j];
;                 u32x2 w; w.x = pk2(y[0], y[1]); w.y = pk2(y[2], y[3]); o8[ci] = w; }
;         }
	v_pk_add_f32 v[50:51], v[50:51], 1.0 op_sel_hi:[1,0]
	v_pk_add_f32 v[52:53], v[52:53], 1.0 op_sel_hi:[1,0]
	v_pk_add_f32 v[54:55], v[54:55], 1.0 op_sel_hi:[1,0]
	v_pk_add_f32 v[56:57], v[56:57], 1.0 op_sel_hi:[1,0]
	v_pk_add_f32 v[58:59], v[58:59], 1.0 op_sel_hi:[1,0]
	v_pk_add_f32 v[60:61], v[60:61], 1.0 op_sel_hi:[1,0]
	v_pk_add_f32 v[62:63], v[62:63], 1.0 op_sel_hi:[1,0]
	v_pk_add_f32 v[64:65], v[64:65], 1.0 op_sel_hi:[1,0]
	s_waitcnt vmcnt(0)
	v_pk_mul_f32 v[18:19], v[18:19], v[92:93] op_sel_hi:[1,0]
	v_pk_mul_f32 v[20:21], v[20:21], v[92:93] op_sel_hi:[1,0]
	v_pk_mul_f32 v[22:23], v[22:23], v[92:93] op_sel_hi:[1,0]
	v_pk_mul_f32 v[24:25], v[24:25], v[92:93] op_sel_hi:[1,0]
	v_pk_mul_f32 v[26:27], v[26:27], v[92:93] op_sel_hi:[1,0]
	v_pk_mul_f32 v[28:29], v[28:29], v[92:93] op_sel_hi:[1,0]
	v_pk_mul_f32 v[30:31], v[30:31], v[92:93] op_sel_hi:[1,0]
	v_pk_mul_f32 v[32:33], v[32:33], v[92:93] op_sel_hi:[1,0]
	v_pk_mul_f32 v[18:19], v[2:3], v[18:19]
	v_pk_mul_f32 v[20:21], v[4:5], v[20:21]
	v_pk_mul_f32 v[22:23], v[6:7], v[22:23]
	v_pk_mul_f32 v[24:25], v[8:9], v[24:25]
	v_pk_mul_f32 v[26:27], v[10:11], v[26:27]
	v_pk_mul_f32 v[28:29], v[12:13], v[28:29]
	v_pk_mul_f32 v[30:31], v[14:15], v[30:31]
	v_pk_mul_f32 v[32:33], v[16:17], v[32:33]
	v_pk_fma_f32 v[18:19], v[50:51], v[18:19], v[66:67]
	v_pk_fma_f32 v[20:21], v[52:53], v[20:21], v[68:69]
	v_pk_fma_f32 v[22:23], v[54:55], v[22:23], v[70:71]
	v_pk_fma_f32 v[24:25], v[56:57], v[24:25], v[72:73]
	v_pk_fma_f32 v[26:27], v[58:59], v[26:27], v[74:75]
	v_pk_fma_f32 v[28:29], v[60:61], v[28:29], v[76:77]
	v_pk_fma_f32 v[30:31], v[62:63], v[30:31], v[78:79]
	v_pk_fma_f32 v[32:33], v[64:65], v[32:33], v[80:81]
	v_cvt_pk_bf16_f32 v18, v18, v19
	v_cvt_pk_bf16_f32 v19, v20, v21
	v_cvt_pk_bf16_f32 v22, v22, v23
	v_cvt_pk_bf16_f32 v23, v24, v25
	v_cvt_pk_bf16_f32 v26, v26, v27
	v_cvt_pk_bf16_f32 v27, v28, v29
	v_cvt_pk_bf16_f32 v30, v30, v31
	v_cvt_pk_bf16_f32 v31, v32, v33
	global_store_dwordx2 v0, v[18:19], s[20:21]
	global_store_dwordx2 v0, v[22:23], s[20:21] offset:512
	global_store_dwordx2 v0, v[26:27], s[20:21] offset:1024
	global_store_dwordx2 v0, v[30:31], s[20:21] offset:1536
	v_pk_mul_f32 v[34:35], v[34:35], v[94:95] op_sel_hi:[1,0]
	v_pk_mul_f32 v[36:37], v[36:37], v[94:95] op_sel_hi:[1,0]
	v_pk_mul_f32 v[38:39], v[38:39], v[94:95] op_sel_hi:[1,0]
	v_pk_mul_f32 v[40:41], v[40:41], v[94:95] op_sel_hi:[1,0]
	v_pk_mul_f32 v[42:43], v[42:43], v[94:95] op_sel_hi:[1,0]
	v_pk_mul_f32 v[44:45], v[44:45], v[94:95] op_sel_hi:[1,0]
	v_pk_mul_f32 v[46:47], v[46:47], v[94:95] op_sel_hi:[1,0]
	v_pk_mul_f32 v[48:49], v[48:49], v[94:95] op_sel_hi:[1,0]
	v_pk_mul_f32 v[34:35], v[2:3], v[34:35]
	v_pk_mul_f32 v[36:37], v[4:5], v[36:37]
	v_pk_mul_f32 v[38:39], v[6:7], v[38:39]
	v_pk_mul_f32 v[40:41], v[8:9], v[40:41]
	v_pk_mul_f32 v[42:43], v[10:11], v[42:43]
	v_pk_mul_f32 v[44:45], v[12:13], v[44:45]
	v_pk_mul_f32 v[46:47], v[14:15], v[46:47]
	v_pk_mul_f32 v[48:49], v[16:17], v[48:49]
	v_pk_fma_f32 v[34:35], v[50:51], v[34:35], v[66:67]
	v_pk_fma_f32 v[36:37], v[52:53], v[36:37], v[68:69]
	v_pk_fma_f32 v[38:39], v[54:55], v[38:39], v[70:71]
	v_pk_fma_f32 v[40:41], v[56:57], v[40:41], v[72:73]
	v_pk_fma_f32 v[42:43], v[58:59], v[42:43], v[74:75]
	v_pk_fma_f32 v[44:45], v[60:61], v[44:45], v[76:77]
	v_pk_fma_f32 v[46:47], v[62:63], v[46:47], v[78:79]
	v_pk_fma_f32 v[48:49], v[64:65], v[48:49], v[80:81]
	v_cvt_pk_bf16_f32 v34, v34, v35
	v_cvt_pk_bf16_f32 v35, v36, v37
	v_cvt_pk_bf16_f32 v38, v38, v39
	v_cvt_pk_bf16_f32 v39, v40, v41
	v_cvt_pk_bf16_f32 v42, v42, v43
	v_cvt_pk_bf16_f32 v43, v44, v45
	v_cvt_pk_bf16_f32 v46, v46, v47
	v_cvt_pk_bf16_f32 v47, v48, v49
	global_store_dwordx2 v0, v[34:35], s[20:21] offset:2048
	global_store_dwordx2 v0, v[38:39], s[20:21] offset:2560
	global_store_dwordx2 v0, v[42:43], s[20:21] offset:3072
	global_store_dwordx2 v0, v[46:47], s[20:21] offset:3584
	s_add_i32 s3, s3, s5
	s_cmp_lt_i32 s3, s4
	s_cbranch_scc1 .Lnorm_loop_p7
